# in-projection GEMM: accumulator zeroing moved into the first K iteration under the LDS-read latency (first half in L1, second half in L2), relaxed first-iteration vmcnt
# speedup vs baseline: 1.0052x; 1.0002x over previous
; #define PG8_STAGE(bufoff, gbase, voff) do { _Pragma("unroll") for (int _i = 0; _i < 2; ++_i) \
;         __builtin_amdgcn_global_load_lds((const unsigned*)((const char*)(gbase) + (voff)[_i]), (LAS unsigned*)(lds + (bufoff) + ldsw + _i * 8192), 16, 0, 0); } while (0)
; #define PG8_LDA(dst, b, h) do { _Pragma("unroll") for (int m = 0; m < 4; ++m) _Pragma("unroll") for (int k = 0; k < 2; ++k) dst[m][k] = *(const LAS bf16x8*)(lds + PG8_SA(b, h) + aoff + m * 2048 + k * 1024); } while (0)
; #define PG8_LDB(dst, b, h) do { _Pragma("unroll") for (int n = 0; n < 2; ++n) _Pragma("unroll") for (int k = 0; k < 2; ++k) dst[n][k] = *(const LAS bf16x8*)(lds + PG8_SB(b, h) + boff + n * 2048 + k * 1024); } while (0)
; #define PG8_MMA(ai, bj, At, Bt) do { __builtin_amdgcn_s_setprio(1); _Pragma("unroll") for (int m = 0; m < 4; ++m) _Pragma("unroll") for (int n = 0; n < 2; ++n) _Pragma("unroll") for (int k = 0; k < 2; ++k) \
;         acc[ai][bj][m][n] = __builtin_amdgcn_mfma_f32_16x16x32_bf16(Bt[n][k], At[m][k], acc[ai][bj][m][n], 0, 0, 0); __builtin_amdgcn_s_setprio(0); } while (0)
; #define PG8_WAIT_V(n) asm volatile("s_waitcnt vmcnt(" #n ")" ::: "memory")
; #define PG8_WAIT_L(n) asm volatile("s_waitcnt lgkmcnt(" #n ")" ::: "memory")
; #define PG8_BAR __builtin_amdgcn_s_barrier()
; #define PG8_SCHED __builtin_amdgcn_sched_barrier(0)
; template <class Epi, class Sched>
; __device__ __forceinline__ void gemm_phase(LAS unsigned char* lds, const Gemm g, const Sched& S, const Epi& E, const int tid) {
;     ...
;         const char* nA = has_next ? (const char*)g.A + (size_t)nxt.pm * tstepA : cA; const char* nB = has_next ? (const char*)g.Bt + (size_t)nxt.pn * tstepB : cB;
;         for (int t = 0; t < nt; t += 2) {
;             const bool last = (t == nt - 2);
;             const char* a1 = cA + (size_t)(t + 1) * kstep;
;             const char* a2 = last ? nA : cA + (size_t)(t + 2) * kstep; const char* b2 = last ? nB : cB + (size_t)(t + 2) * kstep;
;             const char* a3 = a2 + kstep; const char* b3 = b2 + kstep;
;             if constexpr (Epi::HAS_MID) { if (t == 16 || t == 32) E.mid(acc, cur, t, wr, wc, fr, fq); }
;             PG8_LDB(B0, 0, 0); PG8_LDB(B1, 0, 1); PG8_SCHED; PG8_LDA(At, 0, 0); PG8_STAGE(PG8_SA(1, 1), a1 + hstepA, voffA);
;             PG8_WAIT_V(8); PG8_WAIT_L(0); PG8_BAR; PG8_MMA(0, 0, At, B0); PG8_MMA(0, 1, At, B1); PG8_BAR; PG8_SCHED;
.LBB0_346:
	s_ashr_i32 s31, s30, 31
	s_lshl_b64 s[20:21], s[30:31], 20
	s_add_u32 s40, s27, s20
	s_addc_u32 s41, s28, s21
	s_and_b64 s[20:21], s[36:37], exec
	s_cselect_b32 s15, s41, s3
	s_cselect_b32 s16, s40, s2
	s_ashr_i32 s11, s10, 31
	s_lshl_b64 s[20:21], s[10:11], 20
	s_add_u32 s42, s50, s20
	s_addc_u32 s43, s51, s21
	s_and_b64 s[20:21], s[36:37], exec
	s_cselect_b32 s11, s43, s39
	s_cselect_b32 s19, s42, s38
	s_add_u32 s2, s2, 0x80080
	s_addc_u32 s3, s3, 0
	s_add_u32 s20, s38, 0x100
	s_addc_u32 s21, s39, 0
	s_mov_b32 s22, -2
	.p2align	6
.LBB0_347:
	s_add_u32 s24, s2, 0xfff80080
	s_addc_u32 s26, s3, -1
	s_add_i32 s31, 0, 0x10000
	s_cmp_eq_u32 s22, 28
	s_cselect_b32 s49, s15, s26
	s_cselect_b32 s48, s16, s24
	s_cselect_b32 s39, s11, s21
	s_cselect_b32 s38, s19, s20
	s_add_i32 s24, 0, 0x14000
	v_add_u32_e32 v140, s31, v158
	v_add_u32_e32 v154, s24, v158
	ds_read_b128 v[128:131], v140
	ds_read_b128 v[132:135], v140 offset:1024
	ds_read_b128 v[136:139], v140 offset:2048
	ds_read_b128 v[140:143], v140 offset:3072
	ds_read_b128 v[160:163], v154
	ds_read_b128 v[164:167], v154 offset:1024
	ds_read_b128 v[168:171], v154 offset:2048
	ds_read_b128 v[172:175], v154 offset:3072
	v_lshl_add_u64 v[154:155], s[2:3], 0, v[150:151]
	s_add_i32 m0, s45, 0xc000
	ds_read_b128 v[176:179], v159
	ds_read_b128 v[180:183], v159 offset:1024
	ds_read_b128 v[184:187], v159 offset:2048
	ds_read_b128 v[188:191], v159 offset:3072
	ds_read_b128 v[202:205], v159 offset:4096
	ds_read_b128 v[206:209], v159 offset:5120
	ds_read_b128 v[210:213], v159 offset:6144
	ds_read_b128 v[214:217], v159 offset:7168
	global_load_lds_dwordx4 v[154:155], off
	v_lshl_add_u64 v[154:155], s[2:3], 0, v[152:153]
	s_add_i32 m0, s45, 0xe000
	s_nop 0
	global_load_lds_dwordx4 v[154:155], off
	s_cmp_lg_u32 s22, -2
	s_cbranch_scc1 .Lgz3_nf1
	v_mov_b64_e32 v[64:65], 0
	v_mov_b64_e32 v[66:67], 0
	v_mov_b64_e32 v[68:69], 0
	v_mov_b64_e32 v[70:71], 0
	v_mov_b64_e32 v[72:73], 0
	v_mov_b64_e32 v[74:75], 0
	v_mov_b64_e32 v[76:77], 0
	v_mov_b64_e32 v[78:79], 0
	v_mov_b64_e32 v[80:81], 0
	v_mov_b64_e32 v[82:83], 0
	v_mov_b64_e32 v[84:85], 0
	v_mov_b64_e32 v[86:87], 0
	v_mov_b64_e32 v[88:89], 0
	v_mov_b64_e32 v[90:91], 0
	v_mov_b64_e32 v[92:93], 0
	v_mov_b64_e32 v[94:95], 0
	v_mov_b64_e32 v[96:97], 0
	v_mov_b64_e32 v[98:99], 0
	v_mov_b64_e32 v[100:101], 0
	v_mov_b64_e32 v[102:103], 0
	v_mov_b64_e32 v[104:105], 0
	v_mov_b64_e32 v[106:107], 0
	v_mov_b64_e32 v[108:109], 0
	v_mov_b64_e32 v[110:111], 0
	v_mov_b64_e32 v[112:113], 0
	v_mov_b64_e32 v[114:115], 0
	v_mov_b64_e32 v[116:117], 0
	v_mov_b64_e32 v[118:119], 0
	v_mov_b64_e32 v[120:121], 0
	v_mov_b64_e32 v[122:123], 0
	v_mov_b64_e32 v[124:125], 0
	v_mov_b64_e32 v[126:127], 0
	s_waitcnt vmcnt(18)
	s_branch .Lgz3_jn1
.Lgz3_nf1:
	s_waitcnt vmcnt(8)
; #define PG8_STAGE(bufoff, gbase, voff) do { _Pragma("unroll") for (int _i = 0; _i < 2; ++_i) \
;         __builtin_amdgcn_global_load_lds((const unsigned*)((const char*)(gbase) + (voff)[_i]), (LAS unsigned*)(lds + (bufoff) + ldsw + _i * 8192), 16, 0, 0); } while (0)
; #define PG8_LDA(dst, b, h) do { _Pragma("unroll") for (int m = 0; m < 4; ++m) _Pragma("unroll") for (int k = 0; k < 2; ++k) dst[m][k] = *(const LAS bf16x8*)(lds + PG8_SA(b, h) + aoff + m * 2048 + k * 1024); } while (0)
; #define PG8_MMA(ai, bj, At, Bt) do { __builtin_amdgcn_s_setprio(1); _Pragma("unroll") for (int m = 0; m < 4; ++m) _Pragma("unroll") for (int n = 0; n < 2; ++n) _Pragma("unroll") for (int k = 0; k < 2; ++k) \
;         acc[ai][bj][m][n] = __builtin_amdgcn_mfma_f32_16x16x32_bf16(Bt[n][k], At[m][k], acc[ai][bj][m][n], 0, 0, 0); __builtin_amdgcn_s_setprio(0); } while (0)
; #define PG8_WAIT_V(n) asm volatile("s_waitcnt vmcnt(" #n ")" ::: "memory")
; #define PG8_WAIT_L(n) asm volatile("s_waitcnt lgkmcnt(" #n ")" ::: "memory")
; #define PG8_BAR __builtin_amdgcn_s_barrier()
; #define PG8_SCHED __builtin_amdgcn_sched_barrier(0)
; template <class Epi, class Sched>
; __device__ __forceinline__ void gemm_phase(LAS unsigned char* lds, const Gemm g, const Sched& S, const Epi& E, const int tid) {
;     ...
;             PG8_WAIT_V(8); PG8_WAIT_L(0); PG8_BAR; PG8_MMA(0, 0, At, B0); PG8_MMA(0, 1, At, B1); PG8_BAR; PG8_SCHED;
;             PG8_LDA(At, 0, 1); PG8_STAGE(PG8_SB(0, 0), b2, voffB); PG8_STAGE(PG8_SB(0, 1), b2 + hstepB, voffB); PG8_STAGE(PG8_SA(0, 0), a2, voffA);
;             PG8_WAIT_V(8); PG8_WAIT_L(0); PG8_BAR; PG8_MMA(1, 0, At, B0); PG8_MMA(1, 1, At, B1); PG8_BAR; PG8_SCHED;
.Lgz3_jn1:
	s_waitcnt lgkmcnt(0)
	s_barrier
	s_waitcnt lgkmcnt(0)
	v_mfma_f32_16x16x32_bf16 v[124:127], v[128:131], v[176:179], v[124:127]
	v_mfma_f32_16x16x32_bf16 v[120:123], v[136:139], v[176:179], v[120:123]
	v_mfma_f32_16x16x32_bf16 v[108:111], v[128:131], v[184:187], v[108:111]
	v_lshl_add_u64 v[154:155], s[38:39], 0, v[192:193]
	v_mfma_f32_16x16x32_bf16 v[104:107], v[136:139], v[184:187], v[104:107]
	v_mfma_f32_16x16x32_bf16 v[92:95], v[128:131], v[202:205], v[92:95]
	v_mfma_f32_16x16x32_bf16 v[88:91], v[136:139], v[202:205], v[88:91]
	s_add_u32 s64, s38, 0x80000
	s_addc_u32 s65, s39, 0
	v_mfma_f32_16x16x32_bf16 v[76:79], v[128:131], v[210:213], v[76:79]
	v_mfma_f32_16x16x32_bf16 v[72:75], v[136:139], v[210:213], v[72:75]
	v_mfma_f32_16x16x32_bf16 v[124:127], v[132:135], v[180:183], v[124:127]
	v_lshl_add_u64 v[218:219], s[38:39], 0, v[148:149]
	v_mfma_f32_16x16x32_bf16 v[120:123], v[140:143], v[180:183], v[120:123]
	v_mfma_f32_16x16x32_bf16 v[108:111], v[132:135], v[188:191], v[108:111]
	v_mfma_f32_16x16x32_bf16 v[104:107], v[140:143], v[188:191], v[104:107]
	v_mfma_f32_16x16x32_bf16 v[92:95], v[132:135], v[206:209], v[92:95]
	v_lshl_add_u64 v[236:237], s[64:65], 0, v[192:193]
	v_mfma_f32_16x16x32_bf16 v[88:91], v[140:143], v[206:209], v[88:91]
	v_mfma_f32_16x16x32_bf16 v[76:79], v[132:135], v[214:217], v[76:79]
	v_mfma_f32_16x16x32_bf16 v[72:75], v[140:143], v[214:217], v[72:75]
	v_mfma_f32_16x16x32_bf16 v[116:119], v[160:163], v[176:179], v[116:119]
	v_mfma_f32_16x16x32_bf16 v[112:115], v[168:171], v[176:179], v[112:115]
	v_lshl_add_u64 v[238:239], s[64:65], 0, v[148:149]
	v_mfma_f32_16x16x32_bf16 v[100:103], v[160:163], v[184:187], v[100:103]
	v_mfma_f32_16x16x32_bf16 v[96:99], v[168:171], v[184:187], v[96:99]
	v_mfma_f32_16x16x32_bf16 v[84:87], v[160:163], v[202:205], v[84:87]
	v_mfma_f32_16x16x32_bf16 v[80:83], v[168:171], v[202:205], v[80:83]
	v_lshl_add_u64 v[220:221], s[48:49], 0, v[144:145]
	v_mfma_f32_16x16x32_bf16 v[68:71], v[160:163], v[210:213], v[68:71]
	v_mfma_f32_16x16x32_bf16 v[64:67], v[168:171], v[210:213], v[64:67]
	v_mfma_f32_16x16x32_bf16 v[116:119], v[164:167], v[180:183], v[116:119]
	v_mfma_f32_16x16x32_bf16 v[112:115], v[172:175], v[180:183], v[112:115]
	v_lshl_add_u64 v[222:223], s[48:49], 0, v[146:147]
	v_mfma_f32_16x16x32_bf16 v[100:103], v[164:167], v[188:191], v[100:103]
	v_mfma_f32_16x16x32_bf16 v[96:99], v[172:175], v[188:191], v[96:99]
	v_mfma_f32_16x16x32_bf16 v[84:87], v[164:167], v[206:209], v[84:87]
	v_mfma_f32_16x16x32_bf16 v[80:83], v[172:175], v[206:209], v[80:83]
	v_mfma_f32_16x16x32_bf16 v[68:71], v[164:167], v[214:217], v[68:71]
	v_mfma_f32_16x16x32_bf16 v[64:67], v[172:175], v[214:217], v[64:67]
	s_barrier
	s_add_i32 s26, s31, s25
	s_mov_b32 m0, s26
	ds_read_b128 v[176:179], v159 offset:16384
	ds_read_b128 v[180:183], v159 offset:17408
	ds_read_b128 v[184:187], v159 offset:18432
	ds_read_b128 v[188:191], v159 offset:19456
	ds_read_b128 v[202:205], v159 offset:20480
	ds_read_b128 v[206:209], v159 offset:21504
	ds_read_b128 v[210:213], v159 offset:22528
	ds_read_b128 v[214:217], v159 offset:23552
	global_load_lds_dwordx4 v[154:155], off
	s_add_i32 m0, s26, 0x2000
	s_add_i32 s24, s24, s25
	global_load_lds_dwordx4 v[218:219], off
	s_mov_b32 m0, s24
	s_nop 0
	global_load_lds_dwordx4 v[236:237], off
	s_add_i32 m0, s24, 0x2000
	s_nop 0
	global_load_lds_dwordx4 v[238:239], off
	s_mov_b32 m0, s45
	s_nop 0
	global_load_lds_dwordx4 v[220:221], off
	s_mov_b32 m0, s47
	s_nop 0
	global_load_lds_dwordx4 v[222:223], off
	s_cmp_lg_u32 s22, -2
	s_cbranch_scc1 .Lgz3_nf2
	v_mov_b64_e32 v[0:1], 0
	v_mov_b64_e32 v[2:3], 0
	v_mov_b64_e32 v[4:5], 0
	v_mov_b64_e32 v[6:7], 0
	v_mov_b64_e32 v[8:9], 0
	v_mov_b64_e32 v[10:11], 0
	v_mov_b64_e32 v[12:13], 0
	v_mov_b64_e32 v[14:15], 0
	v_mov_b64_e32 v[16:17], 0
	v_mov_b64_e32 v[18:19], 0
	v_mov_b64_e32 v[20:21], 0
	v_mov_b64_e32 v[22:23], 0
	v_mov_b64_e32 v[24:25], 0
	v_mov_b64_e32 v[26:27], 0
	v_mov_b64_e32 v[28:29], 0
	v_mov_b64_e32 v[30:31], 0
	v_mov_b64_e32 v[32:33], 0
	v_mov_b64_e32 v[34:35], 0
	v_mov_b64_e32 v[36:37], 0
	v_mov_b64_e32 v[38:39], 0
	v_mov_b64_e32 v[40:41], 0
	v_mov_b64_e32 v[42:43], 0
	v_mov_b64_e32 v[44:45], 0
	v_mov_b64_e32 v[46:47], 0
	v_mov_b64_e32 v[48:49], 0
	v_mov_b64_e32 v[50:51], 0
	v_mov_b64_e32 v[52:53], 0
	v_mov_b64_e32 v[54:55], 0
	v_mov_b64_e32 v[56:57], 0
	v_mov_b64_e32 v[58:59], 0
	v_mov_b64_e32 v[60:61], 0
	v_mov_b64_e32 v[62:63], 0
	s_waitcnt vmcnt(8)
	s_branch .Lgz3_jn2

; #define PG8_STAGE(bufoff, gbase, voff) do { _Pragma("unroll") for (int _i = 0; _i < 2; ++_i) \
;         __builtin_amdgcn_global_load_lds((const unsigned*)((const char*)(gbase) + (voff)[_i]), (LAS unsigned*)(lds + (bufoff) + ldsw + _i * 8192), 16, 0, 0); } while (0)
; #define PG8_LDA(dst, b, h) do { _Pragma("unroll") for (int m = 0; m < 4; ++m) _Pragma("unroll") for (int k = 0; k < 2; ++k) dst[m][k] = *(const LAS bf16x8*)(lds + PG8_SA(b, h) + aoff + m * 2048 + k * 1024); } while (0)
; #define PG8_LDB(dst, b, h) do { _Pragma("unroll") for (int n = 0; n < 2; ++n) _Pragma("unroll") for (int k = 0; k < 2; ++k) dst[n][k] = *(const LAS bf16x8*)(lds + PG8_SB(b, h) + boff + n * 2048 + k * 1024); } while (0)
; #define PG8_MMA(ai, bj, At, Bt) do { __builtin_amdgcn_s_setprio(1); _Pragma("unroll") for (int m = 0; m < 4; ++m) _Pragma("unroll") for (int n = 0; n < 2; ++n) _Pragma("unroll") for (int k = 0; k < 2; ++k) \
;         acc[ai][bj][m][n] = __builtin_amdgcn_mfma_f32_16x16x32_bf16(Bt[n][k], At[m][k], acc[ai][bj][m][n], 0, 0, 0); __builtin_amdgcn_s_setprio(0); } while (0)
; #define PG8_WAIT_V(n) asm volatile("s_waitcnt vmcnt(" #n ")" ::: "memory")
; #define PG8_WAIT_L(n) asm volatile("s_waitcnt lgkmcnt(" #n ")" ::: "memory")
; #define PG8_BAR __builtin_amdgcn_s_barrier()
; #define PG8_SCHED __builtin_amdgcn_sched_barrier(0)
; template <class Epi, class Sched>
; __device__ __forceinline__ void gemm_phase(LAS unsigned char* lds, const Gemm g, const Sched& S, const Epi& E, const int tid) {
;     ...
;             PG8_WAIT_V(8); PG8_WAIT_L(0); PG8_BAR; PG8_MMA(1, 0, At, B0); PG8_MMA(1, 1, At, B1); PG8_BAR; PG8_SCHED;
;             PG8_LDB(B0, 1, 0); PG8_LDB(B1, 1, 1); PG8_SCHED; PG8_LDA(At, 1, 0); PG8_STAGE(PG8_SA(0, 1), a2 + hstepA, voffA);
;             PG8_WAIT_V(8); PG8_WAIT_L(0); PG8_BAR; PG8_MMA(0, 0, At, B0); PG8_MMA(0, 1, At, B1); PG8_BAR; PG8_SCHED;
.Lgz3_jn2:
	s_waitcnt lgkmcnt(0)
	s_barrier
	s_waitcnt lgkmcnt(0)
	v_mfma_f32_16x16x32_bf16 v[60:63], v[128:131], v[176:179], v[60:63]
	v_mfma_f32_16x16x32_bf16 v[56:59], v[136:139], v[176:179], v[56:59]
	v_mfma_f32_16x16x32_bf16 v[44:47], v[128:131], v[184:187], v[44:47]
	v_mfma_f32_16x16x32_bf16 v[40:43], v[136:139], v[184:187], v[40:43]
	v_mfma_f32_16x16x32_bf16 v[28:31], v[128:131], v[202:205], v[28:31]
	v_mfma_f32_16x16x32_bf16 v[24:27], v[136:139], v[202:205], v[24:27]
	v_mfma_f32_16x16x32_bf16 v[12:15], v[128:131], v[210:213], v[12:15]
	v_mfma_f32_16x16x32_bf16 v[8:11], v[136:139], v[210:213], v[8:11]
	v_mfma_f32_16x16x32_bf16 v[60:63], v[132:135], v[180:183], v[60:63]
	v_mfma_f32_16x16x32_bf16 v[56:59], v[140:143], v[180:183], v[56:59]
	v_mfma_f32_16x16x32_bf16 v[44:47], v[132:135], v[188:191], v[44:47]
	v_mfma_f32_16x16x32_bf16 v[40:43], v[140:143], v[188:191], v[40:43]
	v_mfma_f32_16x16x32_bf16 v[28:31], v[132:135], v[206:209], v[28:31]
	v_mfma_f32_16x16x32_bf16 v[24:27], v[140:143], v[206:209], v[24:27]
	v_mfma_f32_16x16x32_bf16 v[12:15], v[132:135], v[214:217], v[12:15]
	v_mfma_f32_16x16x32_bf16 v[8:11], v[140:143], v[214:217], v[8:11]
	v_mfma_f32_16x16x32_bf16 v[52:55], v[160:163], v[176:179], v[52:55]
	v_mfma_f32_16x16x32_bf16 v[48:51], v[168:171], v[176:179], v[48:51]
	v_mfma_f32_16x16x32_bf16 v[36:39], v[160:163], v[184:187], v[36:39]
	v_mfma_f32_16x16x32_bf16 v[32:35], v[168:171], v[184:187], v[32:35]
	v_mfma_f32_16x16x32_bf16 v[20:23], v[160:163], v[202:205], v[20:23]
	v_mfma_f32_16x16x32_bf16 v[16:19], v[168:171], v[202:205], v[16:19]
	v_mfma_f32_16x16x32_bf16 v[4:7], v[160:163], v[210:213], v[4:7]
	v_mfma_f32_16x16x32_bf16 v[0:3], v[168:171], v[210:213], v[0:3]
	v_mfma_f32_16x16x32_bf16 v[52:55], v[164:167], v[180:183], v[52:55]
	v_mfma_f32_16x16x32_bf16 v[48:51], v[172:175], v[180:183], v[48:51]
	v_mfma_f32_16x16x32_bf16 v[36:39], v[164:167], v[188:191], v[36:39]
	v_mfma_f32_16x16x32_bf16 v[32:35], v[172:175], v[188:191], v[32:35]
	v_mfma_f32_16x16x32_bf16 v[20:23], v[164:167], v[206:209], v[20:23]
	v_mfma_f32_16x16x32_bf16 v[16:19], v[172:175], v[206:209], v[16:19]
	v_mfma_f32_16x16x32_bf16 v[4:7], v[164:167], v[214:217], v[4:7]
	v_mfma_f32_16x16x32_bf16 v[0:3], v[172:175], v[214:217], v[0:3]
	s_barrier
	s_add_i32 s24, 0, 0x18000
	s_add_i32 s26, 0, 0x1c000
	v_add_u32_e32 v140, s24, v158
	v_add_u32_e32 v172, s26, v158
	ds_read_b128 v[128:131], v140
	ds_read_b128 v[132:135], v140 offset:1024
	ds_read_b128 v[136:139], v140 offset:2048
	ds_read_b128 v[140:143], v140 offset:3072
	ds_read_b128 v[160:163], v172
	ds_read_b128 v[164:167], v172 offset:1024
	ds_read_b128 v[168:171], v172 offset:2048
	ds_read_b128 v[172:175], v172 offset:3072
	s_add_u32 s48, s48, 0x80000
	s_addc_u32 s49, s49, 0
	s_mov_b32 m0, s52
	v_lshl_add_u64 v[234:235], s[48:49], 0, v[144:145]
	ds_read_b128 v[176:179], v159 offset:32768
	ds_read_b128 v[180:183], v159 offset:33792
	ds_read_b128 v[184:187], v159 offset:34816
	ds_read_b128 v[188:191], v159 offset:35840
	ds_read_b128 v[202:205], v159 offset:36864
	ds_read_b128 v[206:209], v159 offset:37888
	ds_read_b128 v[210:213], v159 offset:38912
	ds_read_b128 v[214:217], v159 offset:39936
	global_load_lds_dwordx4 v[234:235], off
	v_lshl_add_u64 v[234:235], s[48:49], 0, v[146:147]
	s_mov_b32 m0, s53
	s_nop 0
	global_load_lds_dwordx4 v[234:235], off
	s_waitcnt vmcnt(8)
	s_waitcnt lgkmcnt(0)
	s_barrier
; #define PG8_STAGE(bufoff, gbase, voff) do { _Pragma("unroll") for (int _i = 0; _i < 2; ++_i) \
;         __builtin_amdgcn_global_load_lds((const unsigned*)((const char*)(gbase) + (voff)[_i]), (LAS unsigned*)(lds + (bufoff) + ldsw + _i * 8192), 16, 0, 0); } while (0)
; #define PG8_LDA(dst, b, h) do { _Pragma("unroll") for (int m = 0; m < 4; ++m) _Pragma("unroll") for (int k = 0; k < 2; ++k) dst[m][k] = *(const LAS bf16x8*)(lds + PG8_SA(b, h) + aoff + m * 2048 + k * 1024); } while (0)
; #define PG8_MMA(ai, bj, At, Bt) do { __builtin_amdgcn_s_setprio(1); _Pragma("unroll") for (int m = 0; m < 4; ++m) _Pragma("unroll") for (int n = 0; n < 2; ++n) _Pragma("unroll") for (int k = 0; k < 2; ++k) \
;         acc[ai][bj][m][n] = __builtin_amdgcn_mfma_f32_16x16x32_bf16(Bt[n][k], At[m][k], acc[ai][bj][m][n], 0, 0, 0); __builtin_amdgcn_s_setprio(0); } while (0)
; #define PG8_WAIT_V(n) asm volatile("s_waitcnt vmcnt(" #n ")" ::: "memory")
; #define PG8_WAIT_L(n) asm volatile("s_waitcnt lgkmcnt(" #n ")" ::: "memory")
; #define PG8_BAR __builtin_amdgcn_s_barrier()
; #define PG8_SCHED __builtin_amdgcn_sched_barrier(0)
; template <class Epi, class Sched>
; __device__ __forceinline__ void gemm_phase(LAS unsigned char* lds, const Gemm g, const Sched& S, const Epi& E, const int tid) {
;     ...
;             PG8_WAIT_V(8); PG8_WAIT_L(0); PG8_BAR; PG8_MMA(0, 0, At, B0); PG8_MMA(0, 1, At, B1); PG8_BAR; PG8_SCHED;
;             PG8_LDA(At, 1, 1); PG8_STAGE(PG8_SB(1, 0), b3, voffB); PG8_STAGE(PG8_SB(1, 1), b3 + hstepB, voffB); PG8_STAGE(PG8_SA(1, 0), a3, voffA);
;             PG8_WAIT_V(8); PG8_WAIT_L(0); PG8_BAR; PG8_MMA(1, 0, At, B0); PG8_MMA(1, 1, At, B1); PG8_BAR; PG8_SCHED;
;         }
;         if (wr == 0) PG8_BAR;
	s_waitcnt lgkmcnt(0)
	v_mfma_f32_16x16x32_bf16 v[124:127], v[128:131], v[176:179], v[124:127]
	v_mfma_f32_16x16x32_bf16 v[120:123], v[136:139], v[176:179], v[120:123]
	v_mfma_f32_16x16x32_bf16 v[108:111], v[128:131], v[184:187], v[108:111]
	v_lshl_add_u64 v[154:155], v[154:155], 0, s[34:35]
	v_mfma_f32_16x16x32_bf16 v[104:107], v[136:139], v[184:187], v[104:107]
	v_mfma_f32_16x16x32_bf16 v[92:95], v[128:131], v[202:205], v[92:95]
	v_mfma_f32_16x16x32_bf16 v[88:91], v[136:139], v[202:205], v[88:91]
	s_add_u32 s38, s38, 0x80080
	s_addc_u32 s39, s39, 0
	v_mfma_f32_16x16x32_bf16 v[76:79], v[128:131], v[210:213], v[76:79]
	v_mfma_f32_16x16x32_bf16 v[72:75], v[136:139], v[210:213], v[72:75]
	v_mfma_f32_16x16x32_bf16 v[124:127], v[132:135], v[180:183], v[124:127]
	v_lshl_add_u64 v[240:241], v[218:219], 0, s[34:35]
	v_mfma_f32_16x16x32_bf16 v[120:123], v[140:143], v[180:183], v[120:123]
	v_mfma_f32_16x16x32_bf16 v[108:111], v[132:135], v[188:191], v[108:111]
	v_mfma_f32_16x16x32_bf16 v[104:107], v[140:143], v[188:191], v[104:107]
	v_mfma_f32_16x16x32_bf16 v[92:95], v[132:135], v[206:209], v[92:95]
	v_lshl_add_u64 v[242:243], s[38:39], 0, v[192:193]
	v_mfma_f32_16x16x32_bf16 v[88:91], v[140:143], v[206:209], v[88:91]
	v_mfma_f32_16x16x32_bf16 v[76:79], v[132:135], v[214:217], v[76:79]
	v_mfma_f32_16x16x32_bf16 v[72:75], v[140:143], v[214:217], v[72:75]
	v_mfma_f32_16x16x32_bf16 v[116:119], v[160:163], v[176:179], v[116:119]
	v_mfma_f32_16x16x32_bf16 v[112:115], v[168:171], v[176:179], v[112:115]
	v_lshl_add_u64 v[244:245], s[38:39], 0, v[148:149]
	v_mfma_f32_16x16x32_bf16 v[100:103], v[160:163], v[184:187], v[100:103]
	v_mfma_f32_16x16x32_bf16 v[96:99], v[168:171], v[184:187], v[96:99]
	v_mfma_f32_16x16x32_bf16 v[84:87], v[160:163], v[202:205], v[84:87]
	v_mfma_f32_16x16x32_bf16 v[80:83], v[168:171], v[202:205], v[80:83]
	v_lshl_add_u64 v[246:247], v[220:221], 0, s[34:35]
	v_mfma_f32_16x16x32_bf16 v[68:71], v[160:163], v[210:213], v[68:71]
	v_mfma_f32_16x16x32_bf16 v[64:67], v[168:171], v[210:213], v[64:67]
	v_mfma_f32_16x16x32_bf16 v[116:119], v[164:167], v[180:183], v[116:119]
	v_mfma_f32_16x16x32_bf16 v[112:115], v[172:175], v[180:183], v[112:115]
	v_lshl_add_u64 v[248:249], v[222:223], 0, s[34:35]
	v_mfma_f32_16x16x32_bf16 v[100:103], v[164:167], v[188:191], v[100:103]
	v_mfma_f32_16x16x32_bf16 v[96:99], v[172:175], v[188:191], v[96:99]
	v_mfma_f32_16x16x32_bf16 v[84:87], v[164:167], v[206:209], v[84:87]
	v_mfma_f32_16x16x32_bf16 v[80:83], v[172:175], v[206:209], v[80:83]
	v_mfma_f32_16x16x32_bf16 v[68:71], v[164:167], v[214:217], v[68:71]
	v_mfma_f32_16x16x32_bf16 v[64:67], v[172:175], v[214:217], v[64:67]
	s_barrier
	s_add_i32 s24, s24, s25
	s_mov_b32 m0, s24
	ds_read_b128 v[176:179], v159 offset:49152
	ds_read_b128 v[180:183], v159 offset:50176
	ds_read_b128 v[184:187], v159 offset:51200
	ds_read_b128 v[188:191], v159 offset:52224
	ds_read_b128 v[202:205], v159 offset:53248
	ds_read_b128 v[206:209], v159 offset:54272
	ds_read_b128 v[210:213], v159 offset:55296
	ds_read_b128 v[214:217], v159 offset:56320
	global_load_lds_dwordx4 v[154:155], off
	s_add_i32 m0, s24, 0x2000
	s_add_i32 s24, s26, s25
	global_load_lds_dwordx4 v[240:241], off
	s_mov_b32 m0, s24
	s_nop 0
	global_load_lds_dwordx4 v[242:243], off
	s_add_i32 m0, s24, 0x2000
	s_nop 0
	global_load_lds_dwordx4 v[244:245], off
	s_mov_b32 m0, s56
	s_nop 0
	global_load_lds_dwordx4 v[246:247], off
	s_mov_b32 m0, s57
	s_nop 0
	global_load_lds_dwordx4 v[248:249], off
	s_waitcnt vmcnt(8)
	s_waitcnt lgkmcnt(0)
	s_barrier
	s_waitcnt lgkmcnt(0)
	v_mfma_f32_16x16x32_bf16 v[60:63], v[128:131], v[176:179], v[60:63]
	v_mfma_f32_16x16x32_bf16 v[56:59], v[136:139], v[176:179], v[56:59]
	v_mfma_f32_16x16x32_bf16 v[44:47], v[128:131], v[184:187], v[44:47]
	v_mfma_f32_16x16x32_bf16 v[40:43], v[136:139], v[184:187], v[40:43]
	v_mfma_f32_16x16x32_bf16 v[28:31], v[128:131], v[202:205], v[28:31]
	v_mfma_f32_16x16x32_bf16 v[24:27], v[136:139], v[202:205], v[24:27]
	v_mfma_f32_16x16x32_bf16 v[12:15], v[128:131], v[210:213], v[12:15]
	v_mfma_f32_16x16x32_bf16 v[8:11], v[136:139], v[210:213], v[8:11]
	v_mfma_f32_16x16x32_bf16 v[60:63], v[132:135], v[180:183], v[60:63]
	v_mfma_f32_16x16x32_bf16 v[56:59], v[140:143], v[180:183], v[56:59]
	v_mfma_f32_16x16x32_bf16 v[44:47], v[132:135], v[188:191], v[44:47]
	v_mfma_f32_16x16x32_bf16 v[40:43], v[140:143], v[188:191], v[40:43]
	v_mfma_f32_16x16x32_bf16 v[28:31], v[132:135], v[206:209], v[28:31]
	v_mfma_f32_16x16x32_bf16 v[24:27], v[140:143], v[206:209], v[24:27]
	v_mfma_f32_16x16x32_bf16 v[12:15], v[132:135], v[214:217], v[12:15]
	v_mfma_f32_16x16x32_bf16 v[8:11], v[140:143], v[214:217], v[8:11]
	v_mfma_f32_16x16x32_bf16 v[52:55], v[160:163], v[176:179], v[52:55]
	v_mfma_f32_16x16x32_bf16 v[48:51], v[168:171], v[176:179], v[48:51]
	v_mfma_f32_16x16x32_bf16 v[36:39], v[160:163], v[184:187], v[36:39]
	v_mfma_f32_16x16x32_bf16 v[32:35], v[168:171], v[184:187], v[32:35]
	v_mfma_f32_16x16x32_bf16 v[20:23], v[160:163], v[202:205], v[20:23]
	v_mfma_f32_16x16x32_bf16 v[16:19], v[168:171], v[202:205], v[16:19]
	v_mfma_f32_16x16x32_bf16 v[4:7], v[160:163], v[210:213], v[4:7]
	v_mfma_f32_16x16x32_bf16 v[0:3], v[168:171], v[210:213], v[0:3]
	v_mfma_f32_16x16x32_bf16 v[52:55], v[164:167], v[180:183], v[52:55]
	v_mfma_f32_16x16x32_bf16 v[48:51], v[172:175], v[180:183], v[48:51]
	v_mfma_f32_16x16x32_bf16 v[36:39], v[164:167], v[188:191], v[36:39]
	v_mfma_f32_16x16x32_bf16 v[32:35], v[172:175], v[188:191], v[32:35]
	v_mfma_f32_16x16x32_bf16 v[20:23], v[164:167], v[206:209], v[20:23]
	v_mfma_f32_16x16x32_bf16 v[16:19], v[172:175], v[206:209], v[16:19]
	v_mfma_f32_16x16x32_bf16 v[4:7], v[164:167], v[214:217], v[4:7]
	v_mfma_f32_16x16x32_bf16 v[0:3], v[172:175], v[214:217], v[0:3]
	s_barrier
	s_add_i32 s22, s22, 2
	s_add_u32 s2, s2, 0x100
	s_addc_u32 s3, s3, 0
	s_add_u32 s20, s20, 0x100
	s_addc_u32 s21, s21, 0
	s_cmp_gt_u32 s22, 29
	s_cbranch_scc0 .LBB0_347
	s_and_b64 vcc, exec, s[8:9]
	s_cbranch_vccz .LBB0_350
	s_barrier
